# sample cross-attention: q row load waited at its first consumer (behind the first K rows' counted wait) instead of before the K requests
# speedup vs baseline: 1.0013x; 1.0006x over previous
.LBB11_2191:
	s_ashr_i32 s0, s71, 2
	s_add_i32 s10, s0, 0x4000
	s_ashr_i32 s11, s10, 31
	s_lshl_b64 s[88:89], s[10:11], 10
	s_lshl_b64 s[10:11], s[10:11], 11
	s_add_u32 s1, s6, s10
	s_addc_u32 s11, s7, s11
	s_lshl_b32 s10, s71, 8
	s_and_b32 s68, s10, 0x300
	s_lshl_b32 s10, s68, 1
	s_add_u32 s10, s1, s10
	s_addc_u32 s11, s11, 0
	v_lshl_add_u64 v[176:177], v[100:101], 1, s[10:11]
	s_barrier
	global_load_dwordx2 v[176:177], v[176:177], off
	s_ashr_i32 s1, s0, 31
	s_lshl_b64 s[0:1], s[0:1], 18
	s_add_u32 s0, s0, s70
	s_addc_u32 s1, s1, 0
	s_lshl_b64 s[90:91], s[0:1], 2
	s_add_u32 s0, s56, s90
	s_addc_u32 s1, s57, s91
	s_lshl_b32 s10, s68, 2
	s_add_u32 s0, s0, s10
	s_addc_u32 s1, s1, 0
	v_lshl_add_u64 v[62:63], v[100:101], 2, s[0:1]
	s_mov_b32 s0, 0
	s_mov_b64 s[10:11], -1
	s_branch .LBB11_2193

.LBB11_2193:
	s_lshl_b32 s1, s0, 4
	s_or_b32 s60, s1, s76
	s_lshl_b64 s[48:49], s[60:61], 12
	s_waitcnt lgkmcnt(0)
	v_lshl_add_u64 v[2:3], v[62:63], 0, s[48:49]
	s_or_b32 s48, s60, 1
	s_mov_b32 s49, s61
	s_lshl_b64 s[48:49], s[48:49], 12
	v_lshl_add_u64 v[4:5], v[62:63], 0, s[48:49]
	global_load_dwordx4 v[68:71], v[2:3], off nt
	global_load_dwordx4 v[58:61], v[4:5], off nt
	s_or_b32 s48, s60, 2
	s_mov_b32 s49, s61
	s_lshl_b64 s[48:49], s[48:49], 12
	v_lshl_add_u64 v[2:3], v[62:63], 0, s[48:49]
	s_or_b32 s48, s60, 3
	s_mov_b32 s49, s61
	s_lshl_b64 s[48:49], s[48:49], 12
	v_lshl_add_u64 v[4:5], v[62:63], 0, s[48:49]
	s_or_b32 s48, s60, 4
	s_mov_b32 s49, s61
	s_lshl_b64 s[48:49], s[48:49], 12
	global_load_dwordx4 v[54:57], v[2:3], off nt
	global_load_dwordx4 v[50:53], v[4:5], off nt
	v_lshl_add_u64 v[2:3], v[62:63], 0, s[48:49]
	s_or_b32 s48, s60, 5
	s_mov_b32 s49, s61
	s_lshl_b64 s[48:49], s[48:49], 12
	v_lshl_add_u64 v[4:5], v[62:63], 0, s[48:49]
	s_or_b32 s48, s60, 6
	s_mov_b32 s49, s61
	s_lshl_b64 s[48:49], s[48:49], 12
	global_load_dwordx4 v[46:49], v[2:3], off nt
	global_load_dwordx4 v[42:45], v[4:5], off nt
	v_lshl_add_u64 v[2:3], v[62:63], 0, s[48:49]
	s_or_b32 s48, s60, 7
	s_mov_b32 s49, s61
	s_lshl_b64 s[48:49], s[48:49], 12
	v_lshl_add_u64 v[4:5], v[62:63], 0, s[48:49]
	s_or_b32 s48, s60, 8
	s_mov_b32 s49, s61
	s_lshl_b64 s[48:49], s[48:49], 12
	global_load_dwordx4 v[38:41], v[2:3], off nt
	global_load_dwordx4 v[34:37], v[4:5], off nt
	v_lshl_add_u64 v[2:3], v[62:63], 0, s[48:49]
	s_or_b32 s48, s60, 9
	s_mov_b32 s49, s61
	s_lshl_b64 s[48:49], s[48:49], 12
	v_lshl_add_u64 v[4:5], v[62:63], 0, s[48:49]
	s_or_b32 s48, s60, 10
	s_mov_b32 s49, s61
	s_lshl_b64 s[48:49], s[48:49], 12
	global_load_dwordx4 v[30:33], v[2:3], off nt
	global_load_dwordx4 v[26:29], v[4:5], off nt
	v_lshl_add_u64 v[2:3], v[62:63], 0, s[48:49]
	s_or_b32 s48, s60, 11
	s_mov_b32 s49, s61
	s_lshl_b64 s[48:49], s[48:49], 12
	v_lshl_add_u64 v[4:5], v[62:63], 0, s[48:49]
	s_or_b32 s48, s60, 12
	s_mov_b32 s49, s61
	s_lshl_b64 s[48:49], s[48:49], 12
	global_load_dwordx4 v[22:25], v[2:3], off nt
	global_load_dwordx4 v[18:21], v[4:5], off nt
	v_lshl_add_u64 v[2:3], v[62:63], 0, s[48:49]
	s_or_b32 s48, s60, 13
	s_mov_b32 s49, s61
	s_lshl_b64 s[48:49], s[48:49], 12
	v_lshl_add_u64 v[4:5], v[62:63], 0, s[48:49]
	s_or_b32 s48, s60, 14
	s_mov_b32 s49, s61
	s_lshl_b64 s[48:49], s[48:49], 12
	s_or_b32 s60, s60, 15
	global_load_dwordx4 v[14:17], v[2:3], off nt
	global_load_dwordx4 v[10:13], v[4:5], off nt
	v_lshl_add_u64 v[2:3], v[62:63], 0, s[48:49]
	s_lshl_b64 s[48:49], s[60:61], 12
	v_lshl_add_u64 v[4:5], v[62:63], 0, s[48:49]
	global_load_dwordx4 v[6:9], v[2:3], off nt
	s_nop 0
	global_load_dwordx4 v[2:5], v[4:5], off nt
	s_lshl_b32 s60, s0, 6
	s_waitcnt vmcnt(15)
	v_lshlrev_b32_e32 v64, 16, v176
	v_and_b32_e32 v65, 0xffff0000, v176
	v_lshlrev_b32_e32 v66, 16, v177
	v_and_b32_e32 v67, 0xffff0000, v177
	v_mul_f32_e32 v69, v69, v65
	v_mul_f32_e32 v71, v71, v67
	v_fmac_f32_e32 v69, v68, v64
	v_fmac_f32_e32 v71, v70, v66
	v_add_f32_e32 v68, v69, v71
	s_waitcnt vmcnt(14)
	v_mul_f32_e32 v59, v59, v65
	v_fmac_f32_e32 v59, v58, v64
	v_mul_f32_e32 v58, v61, v67
	v_fmac_f32_e32 v58, v60, v66
	v_add_f32_e32 v58, v59, v58
	s_waitcnt vmcnt(13)
	v_mul_f32_e32 v55, v55, v65
	v_fmac_f32_e32 v55, v54, v64
	v_mul_f32_e32 v54, v57, v67
	v_fmac_f32_e32 v54, v56, v66
	v_add_f32_e32 v54, v55, v54
	s_waitcnt vmcnt(12)
	v_mul_f32_e32 v51, v51, v65
	v_fmac_f32_e32 v51, v50, v64
	v_mul_f32_e32 v50, v53, v67
	v_fmac_f32_e32 v50, v52, v66
	v_add_f32_e32 v50, v51, v50
	s_waitcnt vmcnt(11)
	v_mul_f32_e32 v47, v47, v65
	v_fmac_f32_e32 v47, v46, v64
	v_mul_f32_e32 v46, v49, v67
	v_fmac_f32_e32 v46, v48, v66
	v_add_f32_e32 v46, v47, v46
	s_waitcnt vmcnt(10)
	v_mul_f32_e32 v43, v43, v65
	v_fmac_f32_e32 v43, v42, v64
	v_mul_f32_e32 v42, v45, v67
	v_fmac_f32_e32 v42, v44, v66
	v_add_f32_e32 v42, v43, v42
	s_waitcnt vmcnt(9)
	v_mul_f32_e32 v39, v39, v65
	v_fmac_f32_e32 v39, v38, v64
	v_mul_f32_e32 v38, v41, v67
	v_fmac_f32_e32 v38, v40, v66
	v_add_f32_e32 v38, v39, v38
	s_waitcnt vmcnt(8)
	v_mul_f32_e32 v35, v35, v65
	v_fmac_f32_e32 v35, v34, v64
	v_mul_f32_e32 v34, v37, v67
	v_fmac_f32_e32 v34, v36, v66
	v_add_f32_e32 v34, v35, v34
	s_waitcnt vmcnt(7)
	v_mul_f32_e32 v31, v31, v65
	v_fmac_f32_e32 v31, v30, v64
	v_mul_f32_e32 v30, v33, v67
	v_fmac_f32_e32 v30, v32, v66
	v_add_f32_e32 v30, v31, v30
	s_waitcnt vmcnt(6)
	v_mul_f32_e32 v27, v27, v65
	v_fmac_f32_e32 v27, v26, v64
	v_mul_f32_e32 v26, v29, v67
	v_fmac_f32_e32 v26, v28, v66
	v_add_f32_e32 v26, v27, v26
	s_waitcnt vmcnt(5)
	v_mul_f32_e32 v23, v23, v65
	v_fmac_f32_e32 v23, v22, v64
	v_mul_f32_e32 v22, v25, v67
	v_fmac_f32_e32 v22, v24, v66
	v_add_f32_e32 v22, v23, v22
	s_waitcnt vmcnt(4)
	v_mul_f32_e32 v19, v19, v65
	v_fmac_f32_e32 v19, v18, v64
	v_mul_f32_e32 v18, v21, v67
	v_fmac_f32_e32 v18, v20, v66
	v_add_f32_e32 v18, v19, v18
	s_waitcnt vmcnt(3)
	v_mul_f32_e32 v15, v15, v65
	v_fmac_f32_e32 v15, v14, v64
	v_mul_f32_e32 v14, v17, v67
	v_fmac_f32_e32 v14, v16, v66
	v_add_f32_e32 v14, v15, v14
	s_waitcnt vmcnt(2)
	v_mul_f32_e32 v11, v11, v65
	v_fmac_f32_e32 v11, v10, v64
	v_mul_f32_e32 v10, v13, v67
	v_fmac_f32_e32 v10, v12, v66
	v_add_f32_e32 v10, v11, v10
	s_waitcnt vmcnt(1)
	v_mul_f32_e32 v7, v7, v65
	v_fmac_f32_e32 v7, v6, v64
	v_mul_f32_e32 v6, v9, v67
	v_fmac_f32_e32 v6, v8, v66
	v_add_f32_e32 v6, v7, v6
	s_waitcnt vmcnt(0)
	v_mul_f32_e32 v3, v3, v65
	v_fmac_f32_e32 v3, v2, v64
	v_mul_f32_e32 v2, v5, v67
	v_fmac_f32_e32 v2, v4, v66
	v_add_f32_e32 v2, v3, v2
	ds_bpermute_b32 v69, v200, v68
	ds_bpermute_b32 v59, v200, v58
	ds_bpermute_b32 v55, v200, v54
	ds_bpermute_b32 v51, v200, v50
	ds_bpermute_b32 v47, v200, v46
	ds_bpermute_b32 v43, v200, v42
	ds_bpermute_b32 v39, v200, v38
	ds_bpermute_b32 v35, v200, v34
	s_waitcnt lgkmcnt(7)
	v_add_f32_e32 v68, v68, v69
	s_waitcnt lgkmcnt(6)
	v_add_f32_e32 v58, v58, v59
	s_waitcnt lgkmcnt(5)
	v_add_f32_e32 v54, v54, v55
	s_waitcnt lgkmcnt(4)
	v_add_f32_e32 v50, v50, v51
	s_waitcnt lgkmcnt(3)
	v_add_f32_e32 v46, v46, v47
	s_waitcnt lgkmcnt(2)
	v_add_f32_e32 v42, v42, v43
	s_waitcnt lgkmcnt(1)
	v_add_f32_e32 v38, v38, v39
	s_waitcnt lgkmcnt(0)
	v_add_f32_e32 v34, v34, v35
	ds_bpermute_b32 v69, v201, v68
	ds_bpermute_b32 v59, v201, v58
	ds_bpermute_b32 v55, v201, v54
	ds_bpermute_b32 v51, v201, v50
	ds_bpermute_b32 v47, v201, v46
	ds_bpermute_b32 v43, v201, v42
	ds_bpermute_b32 v39, v201, v38
	ds_bpermute_b32 v35, v201, v34
	s_waitcnt lgkmcnt(7)
	v_add_f32_e32 v68, v68, v69
	s_waitcnt lgkmcnt(6)
	v_add_f32_e32 v58, v58, v59
	s_waitcnt lgkmcnt(5)
	v_add_f32_e32 v54, v54, v55
	s_waitcnt lgkmcnt(4)
	v_add_f32_e32 v50, v50, v51
	s_waitcnt lgkmcnt(3)
	v_add_f32_e32 v46, v46, v47
	s_waitcnt lgkmcnt(2)
	v_add_f32_e32 v42, v42, v43
	s_waitcnt lgkmcnt(1)
	v_add_f32_e32 v38, v38, v39
	s_waitcnt lgkmcnt(0)
	v_add_f32_e32 v34, v34, v35
	ds_bpermute_b32 v69, v202, v68
	ds_bpermute_b32 v59, v202, v58
	ds_bpermute_b32 v55, v202, v54
	ds_bpermute_b32 v51, v202, v50
	ds_bpermute_b32 v47, v202, v46
	ds_bpermute_b32 v43, v202, v42
	ds_bpermute_b32 v39, v202, v38
	ds_bpermute_b32 v35, v202, v34
	s_waitcnt lgkmcnt(7)
	v_add_f32_e32 v68, v68, v69
	s_waitcnt lgkmcnt(6)
	v_add_f32_e32 v58, v58, v59
	s_waitcnt lgkmcnt(5)
	v_add_f32_e32 v54, v54, v55
	s_waitcnt lgkmcnt(4)
	v_add_f32_e32 v50, v50, v51
	s_waitcnt lgkmcnt(3)
	v_add_f32_e32 v46, v46, v47
	s_waitcnt lgkmcnt(2)
	v_add_f32_e32 v42, v42, v43
	s_waitcnt lgkmcnt(1)
	v_add_f32_e32 v38, v38, v39
	s_waitcnt lgkmcnt(0)
	v_add_f32_e32 v34, v34, v35
	ds_bpermute_b32 v69, v203, v68
	ds_bpermute_b32 v59, v203, v58
	ds_bpermute_b32 v55, v203, v54
	ds_bpermute_b32 v51, v203, v50
	ds_bpermute_b32 v47, v203, v46
	ds_bpermute_b32 v43, v203, v42
	ds_bpermute_b32 v39, v203, v38
	ds_bpermute_b32 v35, v203, v34
	s_waitcnt lgkmcnt(7)
	v_add_f32_e32 v68, v68, v69
	s_waitcnt lgkmcnt(6)
	v_add_f32_e32 v58, v58, v59
	s_waitcnt lgkmcnt(5)
	v_add_f32_e32 v54, v54, v55
	s_waitcnt lgkmcnt(4)
	v_add_f32_e32 v50, v50, v51
	s_waitcnt lgkmcnt(3)
	v_add_f32_e32 v46, v46, v47
	s_waitcnt lgkmcnt(2)
	v_add_f32_e32 v42, v42, v43
	s_waitcnt lgkmcnt(1)
	v_add_f32_e32 v38, v38, v39
	s_waitcnt lgkmcnt(0)
	v_add_f32_e32 v34, v34, v35
	ds_bpermute_b32 v69, v204, v68
	ds_bpermute_b32 v59, v204, v58
	ds_bpermute_b32 v55, v204, v54
	ds_bpermute_b32 v51, v204, v50
	ds_bpermute_b32 v47, v204, v46
	ds_bpermute_b32 v43, v204, v42
	ds_bpermute_b32 v39, v204, v38
	ds_bpermute_b32 v35, v204, v34
	s_waitcnt lgkmcnt(7)
	v_add_f32_e32 v68, v68, v69
	s_waitcnt lgkmcnt(6)
	v_add_f32_e32 v58, v58, v59
	s_waitcnt lgkmcnt(5)
	v_add_f32_e32 v54, v54, v55
	s_waitcnt lgkmcnt(4)
	v_add_f32_e32 v50, v50, v51
	s_waitcnt lgkmcnt(3)
	v_add_f32_e32 v46, v46, v47
	s_waitcnt lgkmcnt(2)
	v_add_f32_e32 v42, v42, v43
	s_waitcnt lgkmcnt(1)
	v_add_f32_e32 v38, v38, v39
	s_waitcnt lgkmcnt(0)
	v_add_f32_e32 v34, v34, v35
	ds_bpermute_b32 v69, v205, v68
	ds_bpermute_b32 v59, v205, v58
	ds_bpermute_b32 v55, v205, v54
	ds_bpermute_b32 v51, v205, v50
	ds_bpermute_b32 v47, v205, v46
	ds_bpermute_b32 v43, v205, v42
	ds_bpermute_b32 v39, v205, v38
	ds_bpermute_b32 v35, v205, v34
	s_waitcnt lgkmcnt(7)
	v_add_f32_e32 v68, v68, v69
	s_waitcnt lgkmcnt(6)
	v_add_f32_e32 v58, v58, v59
	s_waitcnt lgkmcnt(5)
	v_add_f32_e32 v54, v54, v55
	s_waitcnt lgkmcnt(4)
	v_add_f32_e32 v50, v50, v51
	s_waitcnt lgkmcnt(3)
	v_add_f32_e32 v46, v46, v47
	s_waitcnt lgkmcnt(2)
	v_add_f32_e32 v42, v42, v43
	s_waitcnt lgkmcnt(1)
	v_add_f32_e32 v38, v38, v39
	s_waitcnt lgkmcnt(0)
	v_add_f32_e32 v34, v34, v35
	ds_bpermute_b32 v31, v200, v30
	ds_bpermute_b32 v27, v200, v26
	ds_bpermute_b32 v23, v200, v22
	ds_bpermute_b32 v19, v200, v18
	ds_bpermute_b32 v15, v200, v14
	ds_bpermute_b32 v11, v200, v10
	ds_bpermute_b32 v7, v200, v6
	ds_bpermute_b32 v3, v200, v2
	s_waitcnt lgkmcnt(7)
	v_add_f32_e32 v30, v30, v31
	s_waitcnt lgkmcnt(6)
	v_add_f32_e32 v26, v26, v27
	s_waitcnt lgkmcnt(5)
	v_add_f32_e32 v22, v22, v23
	s_waitcnt lgkmcnt(4)
	v_add_f32_e32 v18, v18, v19
	s_waitcnt lgkmcnt(3)
	v_add_f32_e32 v14, v14, v15
	s_waitcnt lgkmcnt(2)
	v_add_f32_e32 v10, v10, v11
	s_waitcnt lgkmcnt(1)
	v_add_f32_e32 v6, v6, v7
	s_waitcnt lgkmcnt(0)
	v_add_f32_e32 v2, v2, v3
	ds_bpermute_b32 v31, v201, v30
	ds_bpermute_b32 v27, v201, v26
	ds_bpermute_b32 v23, v201, v22
	ds_bpermute_b32 v19, v201, v18
	ds_bpermute_b32 v15, v201, v14
	ds_bpermute_b32 v11, v201, v10
	ds_bpermute_b32 v7, v201, v6
	ds_bpermute_b32 v3, v201, v2
	s_waitcnt lgkmcnt(7)
	v_add_f32_e32 v30, v30, v31
	s_waitcnt lgkmcnt(6)
	v_add_f32_e32 v26, v26, v27
	s_waitcnt lgkmcnt(5)
	v_add_f32_e32 v22, v22, v23
	s_waitcnt lgkmcnt(4)
	v_add_f32_e32 v18, v18, v19
	s_waitcnt lgkmcnt(3)
	v_add_f32_e32 v14, v14, v15
	s_waitcnt lgkmcnt(2)
	v_add_f32_e32 v10, v10, v11
	s_waitcnt lgkmcnt(1)
	v_add_f32_e32 v6, v6, v7
	s_waitcnt lgkmcnt(0)
	v_add_f32_e32 v2, v2, v3
	ds_bpermute_b32 v31, v202, v30
	ds_bpermute_b32 v27, v202, v26
	ds_bpermute_b32 v23, v202, v22
	ds_bpermute_b32 v19, v202, v18
	ds_bpermute_b32 v15, v202, v14
	ds_bpermute_b32 v11, v202, v10
	ds_bpermute_b32 v7, v202, v6
	ds_bpermute_b32 v3, v202, v2
	s_waitcnt lgkmcnt(7)
	v_add_f32_e32 v30, v30, v31
	s_waitcnt lgkmcnt(6)
	v_add_f32_e32 v26, v26, v27
	s_waitcnt lgkmcnt(5)
	v_add_f32_e32 v22, v22, v23
	s_waitcnt lgkmcnt(4)
	v_add_f32_e32 v18, v18, v19
	s_waitcnt lgkmcnt(3)
	v_add_f32_e32 v14, v14, v15
	s_waitcnt lgkmcnt(2)
	v_add_f32_e32 v10, v10, v11
	s_waitcnt lgkmcnt(1)
	v_add_f32_e32 v6, v6, v7
	s_waitcnt lgkmcnt(0)
	v_add_f32_e32 v2, v2, v3
	ds_bpermute_b32 v31, v203, v30
	ds_bpermute_b32 v27, v203, v26
	ds_bpermute_b32 v23, v203, v22
	ds_bpermute_b32 v19, v203, v18
	ds_bpermute_b32 v15, v203, v14
	ds_bpermute_b32 v11, v203, v10
	ds_bpermute_b32 v7, v203, v6
	ds_bpermute_b32 v3, v203, v2
	s_waitcnt lgkmcnt(7)
	v_add_f32_e32 v30, v30, v31
	s_waitcnt lgkmcnt(6)
	v_add_f32_e32 v26, v26, v27
	s_waitcnt lgkmcnt(5)
	v_add_f32_e32 v22, v22, v23
	s_waitcnt lgkmcnt(4)
	v_add_f32_e32 v18, v18, v19
	s_waitcnt lgkmcnt(3)
	v_add_f32_e32 v14, v14, v15
	s_waitcnt lgkmcnt(2)
	v_add_f32_e32 v10, v10, v11
	s_waitcnt lgkmcnt(1)
	v_add_f32_e32 v6, v6, v7
	s_waitcnt lgkmcnt(0)
	v_add_f32_e32 v2, v2, v3
	ds_bpermute_b32 v31, v204, v30
	ds_bpermute_b32 v27, v204, v26
	ds_bpermute_b32 v23, v204, v22
	ds_bpermute_b32 v19, v204, v18
	ds_bpermute_b32 v15, v204, v14
	ds_bpermute_b32 v11, v204, v10
	ds_bpermute_b32 v7, v204, v6
	ds_bpermute_b32 v3, v204, v2
	s_waitcnt lgkmcnt(7)
	v_add_f32_e32 v30, v30, v31
	s_waitcnt lgkmcnt(6)
	v_add_f32_e32 v26, v26, v27
	s_waitcnt lgkmcnt(5)
	v_add_f32_e32 v22, v22, v23
	s_waitcnt lgkmcnt(4)
	v_add_f32_e32 v18, v18, v19
	s_waitcnt lgkmcnt(3)
	v_add_f32_e32 v14, v14, v15
	s_waitcnt lgkmcnt(2)
	v_add_f32_e32 v10, v10, v11
	s_waitcnt lgkmcnt(1)
	v_add_f32_e32 v6, v6, v7
	s_waitcnt lgkmcnt(0)
	v_add_f32_e32 v2, v2, v3
	ds_bpermute_b32 v31, v205, v30
	ds_bpermute_b32 v27, v205, v26
	ds_bpermute_b32 v23, v205, v22
	ds_bpermute_b32 v19, v205, v18
	ds_bpermute_b32 v15, v205, v14
	ds_bpermute_b32 v11, v205, v10
	ds_bpermute_b32 v7, v205, v6
	ds_bpermute_b32 v3, v205, v2
	s_waitcnt lgkmcnt(7)
	v_add_f32_e32 v30, v30, v31
	s_waitcnt lgkmcnt(6)
	v_add_f32_e32 v26, v26, v27
	s_waitcnt lgkmcnt(5)
	v_add_f32_e32 v22, v22, v23
	s_waitcnt lgkmcnt(4)
	v_add_f32_e32 v18, v18, v19
	s_waitcnt lgkmcnt(3)
	v_add_f32_e32 v14, v14, v15
	s_waitcnt lgkmcnt(2)
	v_add_f32_e32 v10, v10, v11
	s_waitcnt lgkmcnt(1)
	v_add_f32_e32 v6, v6, v7
	s_waitcnt lgkmcnt(0)
	v_add_f32_e32 v2, v2, v3
	s_add_i32 s0, s84, s60
	v_mov_b32_e32 v69, s0
	s_and_saveexec_b64 vcc, s[14:15]
	ds_write_b32 v69, v68
	s_or_b64 exec, exec, vcc
	s_and_saveexec_b64 vcc, s[16:17]
	ds_write_b32 v69, v58 offset:4
	s_or_b64 exec, exec, vcc
	s_and_saveexec_b64 vcc, s[18:19]
	ds_write_b32 v69, v54 offset:8
	s_or_b64 exec, exec, vcc
	s_and_saveexec_b64 vcc, s[20:21]
	ds_write_b32 v69, v50 offset:12
	s_or_b64 exec, exec, vcc
	s_and_saveexec_b64 vcc, s[22:23]
	ds_write_b32 v69, v46 offset:16
	s_or_b64 exec, exec, vcc
	s_and_saveexec_b64 vcc, s[24:25]
	ds_write_b32 v69, v42 offset:20
	s_or_b64 exec, exec, vcc
	s_and_saveexec_b64 vcc, s[26:27]
	ds_write_b32 v69, v38 offset:24
	s_or_b64 exec, exec, vcc
	s_and_saveexec_b64 vcc, s[28:29]
	ds_write_b32 v69, v34 offset:28
	s_or_b64 exec, exec, vcc
	s_and_saveexec_b64 vcc, s[30:31]
	ds_write_b32 v69, v30 offset:32
	s_or_b64 exec, exec, vcc
	s_and_saveexec_b64 vcc, s[34:35]
	ds_write_b32 v69, v26 offset:36
	s_or_b64 exec, exec, vcc
	s_and_saveexec_b64 vcc, s[36:37]
	ds_write_b32 v69, v22 offset:40
	s_or_b64 exec, exec, vcc
	s_and_saveexec_b64 vcc, s[38:39]
	ds_write_b32 v69, v18 offset:44
	s_or_b64 exec, exec, vcc
	s_and_saveexec_b64 vcc, s[40:41]
	ds_write_b32 v69, v14 offset:48
	s_or_b64 exec, exec, vcc
	s_and_saveexec_b64 vcc, s[42:43]
	ds_write_b32 v69, v10 offset:52
	s_or_b64 exec, exec, vcc
	s_and_saveexec_b64 vcc, s[44:45]
	ds_write_b32 v69, v6 offset:56
	s_or_b64 exec, exec, vcc
	s_and_saveexec_b64 vcc, s[46:47]
	ds_write_b32 v69, v2 offset:60
	s_branch .LBB11_2192
